# odd-A: next-unit gate-logit LDS write deferred to unit end (removes mid-unit vmcnt(0) drain of the LDS-DMA prefetch)
# speedup vs baseline: 1.0136x; 1.0107x over previous
; DI void phase_odd_a(const Params& p, LAS unsigned char* lds, int tid, int lane_, int wave, int G) {
;     ...
;         if (more) {
;             oa_dma(PROJ, zeros, lds + OB2_QL, unit + G, tidv, wave);
;             if (part == 0) { const int un = unit + G; const bf16* pr = PROJ + (size_t)((un >> 9) * T_P + ((un >> 3) & 63) * 64 + tl) * ODD_PAD + 4 * DNW + (un & 7); lograw[2 * tl] = pr[0]; lograw[2 * tl + 1] = pr[DNH]; } }
.LBB0_1486:
	s_cmp_eq_u32 s100, 0
	s_cbranch_scc1 .Llograw_skip
	v_and_b32_e32 v253, 7, v0
	v_cmp_eq_u32_e64 s[98:99], 0, v253
	s_and_saveexec_b64 s[100:101], s[98:99]
	s_waitcnt vmcnt(0)
	ds_write2_b32 v252, v250, v251 offset1:1
	s_mov_b64 exec, s[100:101]

; DI void phase_odd_a(const Params& p, LAS unsigned char* lds, int tid, int lane_, int wave, int G) {
;     ...
;     for (int unit = (int)blockIdx.x - G; unit < NB_P * 64 * DNH; unit += G) {
;         int tidv = tid; asm volatile("" : "+v"(tidv));
;         const int lane = tidv & 63, r = lane & 31, h2 = lane >> 5, tl = tidv >> 3, part = tidv & 7;
;         const bool real = unit >= 0, more = unit + G < NB_P * 64 * DNH;
;         const int h = unit & 7, c = (unit >> 3) & 63, b = unit >> 9;
;         if (real) {
;             const int t0 = c * 64, m0 = b * T_P + t0, m = m0 + tl;
;             if (h != curh) { curh = h;
; #pragma unroll
;                 for (int rep = 0; rep < 3; ++rep) { const int id = tidv + 512 * rep, tn = id >> 9, i = (id >> 7) & 3, d = id & 127; cwl[id] = cw[i * 3 * DNW + tn * DNW + h * DND + d]; }
;                 __syncthreads(); }
.LBB0_1487:
	s_mov_b32 s100, 0
	s_add_i32 s8, s66, s81
	v_mov_b32_e32 v155, v0
	s_cmp_gt_i32 s8, -1
	s_cselect_b64 s[34:35], -1, 0
	v_and_b32_e32 v154, 63, v155
	v_and_b32_e32 v156, 31, v155
	v_bfe_u32 v153, v155, 5, 1
	v_ashrrev_i32_e32 v157, 3, v155
	s_cmp_lt_i32 s8, 0
	v_and_b32_e32 v158, 7, v155
	s_cbranch_scc1 .LBB0_1674
	s_and_b32 s36, s8, 7
	s_cmp_eq_u32 s36, s82
	v_and_b32_e32 v1, 0x7f, v155
	s_cbranch_scc1 .LBB0_1490
	v_bfe_u32 v2, v155, 7, 2
	v_mul_u32_u24_e32 v2, 0xc00, v2
	s_lshl_b32 s0, s36, 7
	s_waitcnt lgkmcnt(0)
	v_lshlrev_b32_e32 v5, 1, v155
	v_or3_b32 v4, v2, s0, v1
	v_and_b32_e32 v2, 0xfffffc00, v5
	v_add_u32_e32 v2, v4, v2
	v_readlane_b32 s16, v243, 8
	v_ashrrev_i32_e32 v3, 31, v2
	v_readlane_b32 s26, v243, 18
	v_readlane_b32 s27, v243, 19
	s_mov_b32 s82, s36
	v_readlane_b32 s17, v243, 9
	v_lshl_add_u64 v[2:3], v[2:3], 2, s[26:27]
	global_load_dword v6, v[2:3], off
	v_lshl_add_u32 v2, v155, 2, 0
	v_add_u32_e32 v7, 0x1e800, v2
	v_add_u32_e32 v2, 0x400, v5
	v_and_b32_e32 v2, 0xfffffc00, v2
	v_add_u32_e32 v2, v4, v2
	v_ashrrev_i32_e32 v3, 31, v2
	v_lshl_add_u64 v[2:3], v[2:3], 2, s[26:27]
	global_load_dword v2, v[2:3], off
	v_readlane_b32 s18, v243, 10
	v_readlane_b32 s19, v243, 11
	v_readlane_b32 s20, v243, 12
	v_readlane_b32 s21, v243, 13
	v_readlane_b32 s22, v243, 14
	v_readlane_b32 s23, v243, 15
	v_readlane_b32 s24, v243, 16
	v_readlane_b32 s25, v243, 17
	v_readlane_b32 s28, v243, 20
	v_readlane_b32 s29, v243, 21
	v_readlane_b32 s30, v243, 22
	v_readlane_b32 s31, v243, 23
	s_waitcnt vmcnt(0)
	ds_write2st64_b32 v7, v6, v2 offset1:8
	v_add_u32_e32 v2, 0x800, v5
	v_and_b32_e32 v2, 0xfffffc00, v2
	v_add_u32_e32 v2, v4, v2
	v_ashrrev_i32_e32 v3, 31, v2
	v_lshl_add_u64 v[2:3], v[2:3], 2, s[26:27]
	global_load_dword v2, v[2:3], off
	s_waitcnt vmcnt(0)
	ds_write_b32 v7, v2 offset:4096
	s_waitcnt lgkmcnt(0)
	s_barrier

; #define LAS __attribute__((address_space(3)))
; DI void oa_dma(const bf16* PROJ, const bf16* zeros, LAS unsigned char* rawb, int unit, int tid, int wave) {
;     ...
;     for (int rep = 0; rep < 7; ++rep) { const int id = tid + 512 * rep, row = id / 48, sg = id - row * 48, tn = sg >> 4, ck = sg & 15;
;         const bool valid = id < 67 * 48 && !(c == 0 && row < 3);
;         const bf16* src = valid ? PROJ + (size_t)(m0 - 3 + row) * ODD_PAD + tn * DNW + h * DND + ck * 8 : zeros + (tid & 63) * 8;
;         __builtin_amdgcn_global_load_lds((const unsigned*)src, (LAS unsigned*)(rawb + (512 * rep + 64 * wave) * 16), 16, 0, 0); }
; DI void phase_odd_a(const Params& p, LAS unsigned char* lds, int tid, int lane_, int wave, int G) {
;     ...
;         if (more) {
;             oa_dma(PROJ, zeros, lds + OB2_QL, unit + G, tidv, wave);
;             if (part == 0) { const int un = unit + G; const bf16* pr = PROJ + (size_t)((un >> 9) * T_P + ((un >> 3) & 63) * 64 + tl) * ODD_PAD + 4 * DNW + (un & 7); lograw[2 * tl] = pr[0]; lograw[2 * tl + 1] = pr[DNH]; } }
.LBB0_1689:
	s_or_b64 exec, exec, s[0:1]
	s_add_i32 m0, s50, 0xc000
	v_cmp_eq_u32_e32 vcc, 0, v158
	global_load_lds_dwordx4 v[2:3], off
	s_mov_b32 s100, 1
	s_and_saveexec_b64 s[0:1], vcc
	s_cbranch_execz .LBB0_1691
	v_readlane_b32 s24, v243, 6
	s_and_b32 s36, s80, 0xffffffc0
	v_readlane_b32 s25, v243, 7
	v_add_u32_e32 v1, s36, v157
	s_nop 0
	v_mov_b64_e32 v[2:3], s[24:25]
	v_mad_i64_i32 v[2:3], s[36:37], v1, s55, v[2:3]
	s_and_b32 s36, s81, 7
	s_lshl_b32 s36, s36, 1
	s_mov_b32 s37, s9
	v_lshl_add_u64 v[2:3], v[2:3], 0, s[36:37]
	s_mov_b64 s[36:37], 0x2000
	v_lshl_add_u64 v[4:5], v[2:3], 0, s[36:37]
	v_add_co_u32_e32 v2, vcc, 0x2000, v2
	s_nop 1
	v_addc_co_u32_e32 v3, vcc, 0, v3, vcc
	global_load_ushort v250, v[2:3], off
	s_nop 0
	global_load_ushort v251, v[4:5], off offset:16
	v_add_u32_e32 v252, 0x22400, v155
